# dead K-neighbour register zero-inits removed from the chunk-output phase
# baseline (speedup 1.0000x reference)
.Lkc5_ld:
	global_load_dwordx4 v[96:99], v[2:3], off offset:48
	global_load_dwordx4 v[100:103], v[2:3], off offset:32
	global_load_dwordx4 v[104:107], v[2:3], off offset:16
	global_load_dwordx4 v[108:111], v[2:3], off
	v_cndmask_b32_e64 v4, 0, 1, s[12:13]
	v_and_b32_e32 v249, 0xff, v250
	s_lshl_b32 s36, s42, 6
	v_lshlrev_b32_e32 v247, 5, v251
	v_cmp_ne_u32_e64 s[6:7], 1, v4
	s_andn2_b64 vcc, exec, s[12:13]
	s_cbranch_vccnz .LBB0_514
	s_and_saveexec_b64 s[14:15], s[10:11]
	s_cbranch_execz .LBB0_511
	s_movk_i32 s0, 0xe000
	v_add_co_u32_e32 v6, vcc, 0xffffe000, v2
	s_mov_b32 s1, -1
	s_nop 0
	v_addc_co_u32_e32 v7, vcc, -1, v3, vcc
	v_lshl_add_u64 v[4:5], v[2:3], 0, s[0:1]
.LBB0_511:
	s_or_b64 exec, exec, s[14:15]
	s_and_saveexec_b64 s[10:11], s[8:9]
	s_cbranch_execz .LBB0_513
	s_mov_b64 s[0:1], 0x2000
	v_lshl_add_u64 v[4:5], v[2:3], 0, s[0:1]
	v_add_co_u32_e32 v2, vcc, 0x2000, v2
	s_nop 1
	v_addc_co_u32_e32 v3, vcc, 0, v3, vcc

.LBB0_514:
	s_mov_b64 s[8:9], 0x400
.LBB0_515:
	s_cmp_gt_i32 s38, 1
	s_cselect_b64 s[14:15], -1, 0
	s_lshl_b32 s68, s8, 1
	v_lshl_add_u64 v[0:1], v[0:1], 0, s[68:69]
	global_load_dwordx4 v[48:51], v[0:1], off offset:48
	global_load_dwordx4 v[52:55], v[0:1], off offset:32
	global_load_dwordx4 v[56:59], v[0:1], off offset:16
	global_load_dwordx4 v[60:63], v[0:1], off
	v_and_b32_e32 v252, 63, v250
	v_lshrrev_b32_e32 v253, 6, v249
	s_mov_b64 s[8:9], -1
	s_and_b64 vcc, exec, s[12:13]
	v_readlane_b32 s57, v254, 5
	s_cbranch_vccz .LBB0_525
	s_movk_i32 s0, 0x7f
	v_cmp_lt_u32_e32 vcc, s0, v249
	s_and_saveexec_b64 s[0:1], vcc
	s_xor_b64 s[8:9], exec, s[0:1]
	s_cbranch_execz .LBB0_520
	v_cmp_eq_u32_e32 vcc, 2, v253
	s_and_saveexec_b64 s[10:11], vcc
	s_cbranch_execz .LBB0_519
	v_lshrrev_b32_e32 v2, 5, v252
	s_lshl_b32 s0, s39, 3
	v_lshlrev_b32_e32 v0, 4, v2
	s_or_b32 s0, s0, s42
	v_add3_u32 v3, s0, 32, v0
	s_and_b64 s[0:1], s[14:15], exec
	s_cselect_b32 s0, 0x43, 1
	s_sub_i32 s0, s0, s38
	v_mov_b32_e32 v0, s0
	v_mov_b32_e32 v1, s38
	v_cmp_gt_u32_e32 vcc, 32, v252
	v_lshlrev_b32_e32 v2, 8, v2
	s_nop 0
	v_cndmask_b32_e32 v0, v0, v1, vcc
	v_ashrrev_i32_e32 v1, 31, v0
	v_mad_i64_i32 v[0:1], s[0:1], v3, s90, v[0:1]
	v_lshlrev_b64 v[0:1], 8, v[0:1]
	v_lshlrev_b32_e32 v3, 3, v249
	v_lshl_add_u64 v[0:1], s[24:25], 0, v[0:1]
	v_and_b32_e32 v160, 0xf8, v3
	v_lshl_add_u64 v[0:1], v[0:1], 0, v[160:161]
	global_load_dwordx2 v[0:1], v[0:1], off
	v_readlane_b32 s0, v254, 7
	s_nop 1
	v_add3_u32 v2, s0, v2, v160
	s_waitcnt vmcnt(0)
	ds_write_b64 v2, v[0:1]
